# plus P8 sample-piece epilogue: 32 serialized gate load-wait-store rounds replaced by hoisted loads + counted vmcnt
# speedup vs baseline: 1.0122x; 1.0028x over previous
; __device__ __forceinline__ float bfl(unsigned w) { return __uint_as_float(w << 16); }
; __device__ __forceinline__ float bfh(unsigned w) { return __uint_as_float(w & 0xffff0000u); }
;     __device__ __forceinline__ void operator()(const f32x4 (&acc)[2][2][4][2], const Unit& u, int wr, int wc, int fr, int fq) const {
;         const int slice = u.kt0 / ntsub;
;         const bf16_t* G = (slice >= 4 ? GB : GA) + (size_t)NP * D;
;         float* C = slab + (size_t)slice * ((size_t)NS * D);
;         const int row0 = (u.pm - NP / BM) * BM + wr * 64 + fr, col0 = u.pn * BM + wc * 32 + 4 * fq;
; #pragma unroll
;         for (int ai = 0; ai < 2; ++ai)
; #pragma unroll
;             for (int m = 0; m < 4; ++m) { const size_t ro = (size_t)(row0 + ai * HALF + m * 16) * D + col0;
; #pragma unroll
;                 for (int bj = 0; bj < 2; ++bj)
; #pragma unroll
;                     for (int n = 0; n < 2; ++n) { const size_t o = ro + bj * HALF + n * 16;
;                         const u32x2 gw = *(const u32x2*)(G + o); const f32x4 g = (f32x4){bfl(gw.x), bfh(gw.x), bfl(gw.y), bfh(gw.y)};
;                         *(f32x4*)(C + o) = g * acc[ai][bj][m][n]; }
.LBB0_1222:
	s_ashr_i32 s11, s10, 31
	s_lshr_b32 s11, s11, 29
	s_add_i32 s11, s10, s11
	s_ashr_i32 s36, s11, 3
	s_cmp_gt_i32 s10, 31
	s_cselect_b32 s21, s8, s6
	s_cselect_b32 s11, s9, s7
	s_add_u32 s30, s21, 0x2000000
	s_addc_u32 s31, s11, 0
	s_ashr_i32 s37, s36, 31
	s_lshl_b64 s[36:37], s[36:37], 22
	s_add_u32 s36, s49, s36
	s_addc_u32 s37, s50, s37
	s_mov_b64 s[38:39], 0x40000
	s_andn2_b64 vcc, exec, s[24:25]
	s_mov_b64 s[24:25], -1
	v_lshl_add_u32 v142, s57, 8, v145
	v_lshl_or_b32 v140, s56, 8, v146
	v_lshl_add_u32 v240, v142, 11, v140
	v_lshlrev_b32_e32 v224, 1, v240
	v_lshlrev_b32_e32 v232, 2, v240
	v_add_u32_e32 v225, 0x10000, v224
	v_add_u32_e32 v233, 0x20000, v232
	v_add_u32_e32 v226, 0x20000, v224
	v_add_u32_e32 v234, 0x40000, v232
	v_add_u32_e32 v227, 0x30000, v224
	v_add_u32_e32 v235, 0x60000, v232
	v_add_u32_e32 v228, 0x80000, v224
	v_add_u32_e32 v236, 0x100000, v232
	v_add_u32_e32 v229, 0x90000, v224
	v_add_u32_e32 v237, 0x120000, v232
	v_add_u32_e32 v230, 0xa0000, v224
	v_add_u32_e32 v238, 0x140000, v232
	v_add_u32_e32 v231, 0xb0000, v224
	v_add_u32_e32 v239, 0x160000, v232
	global_load_dwordx2 v[160:161], v224, s[30:31] offset:0
	global_load_dwordx2 v[162:163], v224, s[30:31] offset:32
	global_load_dwordx2 v[164:165], v224, s[30:31] offset:256
	global_load_dwordx2 v[166:167], v224, s[30:31] offset:288
	global_load_dwordx2 v[168:169], v225, s[30:31] offset:0
	global_load_dwordx2 v[170:171], v225, s[30:31] offset:32
	global_load_dwordx2 v[172:173], v225, s[30:31] offset:256
	global_load_dwordx2 v[174:175], v225, s[30:31] offset:288
	global_load_dwordx2 v[176:177], v226, s[30:31] offset:0
	global_load_dwordx2 v[178:179], v226, s[30:31] offset:32
	global_load_dwordx2 v[180:181], v226, s[30:31] offset:256
	global_load_dwordx2 v[182:183], v226, s[30:31] offset:288
	global_load_dwordx2 v[184:185], v227, s[30:31] offset:0
	global_load_dwordx2 v[186:187], v227, s[30:31] offset:32
	global_load_dwordx2 v[188:189], v227, s[30:31] offset:256
	global_load_dwordx2 v[190:191], v227, s[30:31] offset:288
	global_load_dwordx2 v[192:193], v228, s[30:31] offset:0
	global_load_dwordx2 v[194:195], v228, s[30:31] offset:32
	global_load_dwordx2 v[196:197], v228, s[30:31] offset:256
	global_load_dwordx2 v[198:199], v228, s[30:31] offset:288
	global_load_dwordx2 v[200:201], v229, s[30:31] offset:0
	global_load_dwordx2 v[202:203], v229, s[30:31] offset:32
	global_load_dwordx2 v[204:205], v229, s[30:31] offset:256
	global_load_dwordx2 v[206:207], v229, s[30:31] offset:288
	global_load_dwordx2 v[208:209], v230, s[30:31] offset:0
	global_load_dwordx2 v[210:211], v230, s[30:31] offset:32
	global_load_dwordx2 v[212:213], v230, s[30:31] offset:256
	global_load_dwordx2 v[214:215], v230, s[30:31] offset:288
	global_load_dwordx2 v[216:217], v231, s[30:31] offset:0
	global_load_dwordx2 v[218:219], v231, s[30:31] offset:32
	global_load_dwordx2 v[220:221], v231, s[30:31] offset:256
	global_load_dwordx2 v[222:223], v231, s[30:31] offset:288
	s_waitcnt vmcnt(31)
	v_lshlrev_b32_e32 v240, 16, v160
	v_and_b32_e32 v241, 0xffff0000, v160
	v_lshlrev_b32_e32 v242, 16, v161
	v_and_b32_e32 v243, 0xffff0000, v161
	v_pk_mul_f32 v[126:127], v[126:127], v[240:241]
	v_pk_mul_f32 v[128:129], v[128:129], v[242:243]
	global_store_dwordx4 v232, v[126:129], s[36:37] offset:0
	s_waitcnt vmcnt(31)
	v_lshlrev_b32_e32 v240, 16, v162
	v_and_b32_e32 v241, 0xffff0000, v162
	v_lshlrev_b32_e32 v242, 16, v163
	v_and_b32_e32 v243, 0xffff0000, v163
	v_pk_mul_f32 v[122:123], v[122:123], v[240:241]
	v_pk_mul_f32 v[124:125], v[124:125], v[242:243]
	global_store_dwordx4 v232, v[122:125], s[36:37] offset:64
	s_waitcnt vmcnt(31)
	v_lshlrev_b32_e32 v240, 16, v164
	v_and_b32_e32 v241, 0xffff0000, v164
	v_lshlrev_b32_e32 v242, 16, v165
	v_and_b32_e32 v243, 0xffff0000, v165
	v_pk_mul_f32 v[118:119], v[118:119], v[240:241]
	v_pk_mul_f32 v[120:121], v[120:121], v[242:243]
	global_store_dwordx4 v232, v[118:121], s[36:37] offset:512
	s_waitcnt vmcnt(31)
	v_lshlrev_b32_e32 v240, 16, v166
	v_and_b32_e32 v241, 0xffff0000, v166
	v_lshlrev_b32_e32 v242, 16, v167
	v_and_b32_e32 v243, 0xffff0000, v167
	v_pk_mul_f32 v[114:115], v[114:115], v[240:241]
	v_pk_mul_f32 v[116:117], v[116:117], v[242:243]
	global_store_dwordx4 v232, v[114:117], s[36:37] offset:576
	s_waitcnt vmcnt(31)
	v_lshlrev_b32_e32 v240, 16, v168
	v_and_b32_e32 v241, 0xffff0000, v168
	v_lshlrev_b32_e32 v242, 16, v169
	v_and_b32_e32 v243, 0xffff0000, v169
	v_pk_mul_f32 v[110:111], v[110:111], v[240:241]
	v_pk_mul_f32 v[112:113], v[112:113], v[242:243]
	global_store_dwordx4 v233, v[110:113], s[36:37] offset:0
	s_waitcnt vmcnt(31)
	v_lshlrev_b32_e32 v240, 16, v170
	v_and_b32_e32 v241, 0xffff0000, v170
	v_lshlrev_b32_e32 v242, 16, v171
	v_and_b32_e32 v243, 0xffff0000, v171
	v_pk_mul_f32 v[106:107], v[106:107], v[240:241]
	v_pk_mul_f32 v[108:109], v[108:109], v[242:243]
	global_store_dwordx4 v233, v[106:109], s[36:37] offset:64
	s_waitcnt vmcnt(31)
	v_lshlrev_b32_e32 v240, 16, v172
	v_and_b32_e32 v241, 0xffff0000, v172
	v_lshlrev_b32_e32 v242, 16, v173
	v_and_b32_e32 v243, 0xffff0000, v173
	v_pk_mul_f32 v[102:103], v[102:103], v[240:241]
	v_pk_mul_f32 v[104:105], v[104:105], v[242:243]
	global_store_dwordx4 v233, v[102:105], s[36:37] offset:512
	s_waitcnt vmcnt(31)
	v_lshlrev_b32_e32 v240, 16, v174
	v_and_b32_e32 v241, 0xffff0000, v174
	v_lshlrev_b32_e32 v242, 16, v175
	v_and_b32_e32 v243, 0xffff0000, v175
	v_pk_mul_f32 v[98:99], v[98:99], v[240:241]
	v_pk_mul_f32 v[100:101], v[100:101], v[242:243]
	global_store_dwordx4 v233, v[98:101], s[36:37] offset:576
	s_waitcnt vmcnt(31)
; __device__ __forceinline__ float bfl(unsigned w) { return __uint_as_float(w << 16); }
; __device__ __forceinline__ float bfh(unsigned w) { return __uint_as_float(w & 0xffff0000u); }
;     __device__ __forceinline__ void operator()(const f32x4 (&acc)[2][2][4][2], const Unit& u, int wr, int wc, int fr, int fq) const {
;     ...
;         for (int ai = 0; ai < 2; ++ai)
; #pragma unroll
;             for (int m = 0; m < 4; ++m) { const size_t ro = (size_t)(row0 + ai * HALF + m * 16) * D + col0;
; #pragma unroll
;                 for (int bj = 0; bj < 2; ++bj)
; #pragma unroll
;                     for (int n = 0; n < 2; ++n) { const size_t o = ro + bj * HALF + n * 16;
;                         const u32x2 gw = *(const u32x2*)(G + o); const f32x4 g = (f32x4){bfl(gw.x), bfh(gw.x), bfl(gw.y), bfh(gw.y)};
;                         *(f32x4*)(C + o) = g * acc[ai][bj][m][n]; }
	v_lshlrev_b32_e32 v240, 16, v176
	v_and_b32_e32 v241, 0xffff0000, v176
	v_lshlrev_b32_e32 v242, 16, v177
	v_and_b32_e32 v243, 0xffff0000, v177
	v_pk_mul_f32 v[94:95], v[94:95], v[240:241]
	v_pk_mul_f32 v[96:97], v[96:97], v[242:243]
	global_store_dwordx4 v234, v[94:97], s[36:37] offset:0
	s_waitcnt vmcnt(31)
	v_lshlrev_b32_e32 v240, 16, v178
	v_and_b32_e32 v241, 0xffff0000, v178
	v_lshlrev_b32_e32 v242, 16, v179
	v_and_b32_e32 v243, 0xffff0000, v179
	v_pk_mul_f32 v[90:91], v[90:91], v[240:241]
	v_pk_mul_f32 v[92:93], v[92:93], v[242:243]
	global_store_dwordx4 v234, v[90:93], s[36:37] offset:64
	s_waitcnt vmcnt(31)
	v_lshlrev_b32_e32 v240, 16, v180
	v_and_b32_e32 v241, 0xffff0000, v180
	v_lshlrev_b32_e32 v242, 16, v181
	v_and_b32_e32 v243, 0xffff0000, v181
	v_pk_mul_f32 v[86:87], v[86:87], v[240:241]
	v_pk_mul_f32 v[88:89], v[88:89], v[242:243]
	global_store_dwordx4 v234, v[86:89], s[36:37] offset:512
	s_waitcnt vmcnt(31)
	v_lshlrev_b32_e32 v240, 16, v182
	v_and_b32_e32 v241, 0xffff0000, v182
	v_lshlrev_b32_e32 v242, 16, v183
	v_and_b32_e32 v243, 0xffff0000, v183
	v_pk_mul_f32 v[82:83], v[82:83], v[240:241]
	v_pk_mul_f32 v[84:85], v[84:85], v[242:243]
	global_store_dwordx4 v234, v[82:85], s[36:37] offset:576
	s_waitcnt vmcnt(31)
	v_lshlrev_b32_e32 v240, 16, v184
	v_and_b32_e32 v241, 0xffff0000, v184
	v_lshlrev_b32_e32 v242, 16, v185
	v_and_b32_e32 v243, 0xffff0000, v185
	v_pk_mul_f32 v[78:79], v[78:79], v[240:241]
	v_pk_mul_f32 v[80:81], v[80:81], v[242:243]
	global_store_dwordx4 v235, v[78:81], s[36:37] offset:0
	s_waitcnt vmcnt(31)
	v_lshlrev_b32_e32 v240, 16, v186
	v_and_b32_e32 v241, 0xffff0000, v186
	v_lshlrev_b32_e32 v242, 16, v187
	v_and_b32_e32 v243, 0xffff0000, v187
	v_pk_mul_f32 v[74:75], v[74:75], v[240:241]
	v_pk_mul_f32 v[76:77], v[76:77], v[242:243]
	global_store_dwordx4 v235, v[74:77], s[36:37] offset:64
	s_waitcnt vmcnt(31)
	v_lshlrev_b32_e32 v240, 16, v188
	v_and_b32_e32 v241, 0xffff0000, v188
	v_lshlrev_b32_e32 v242, 16, v189
	v_and_b32_e32 v243, 0xffff0000, v189
	v_pk_mul_f32 v[70:71], v[70:71], v[240:241]
	v_pk_mul_f32 v[72:73], v[72:73], v[242:243]
	global_store_dwordx4 v235, v[70:73], s[36:37] offset:512
	s_waitcnt vmcnt(31)
	v_lshlrev_b32_e32 v240, 16, v190
	v_and_b32_e32 v241, 0xffff0000, v190
	v_lshlrev_b32_e32 v242, 16, v191
	v_and_b32_e32 v243, 0xffff0000, v191
	v_pk_mul_f32 v[66:67], v[66:67], v[240:241]
	v_pk_mul_f32 v[68:69], v[68:69], v[242:243]
	global_store_dwordx4 v235, v[66:69], s[36:37] offset:576
	s_waitcnt vmcnt(31)
	v_lshlrev_b32_e32 v240, 16, v192
	v_and_b32_e32 v241, 0xffff0000, v192
	v_lshlrev_b32_e32 v242, 16, v193
	v_and_b32_e32 v243, 0xffff0000, v193
	v_pk_mul_f32 v[62:63], v[62:63], v[240:241]
	v_pk_mul_f32 v[64:65], v[64:65], v[242:243]
	global_store_dwordx4 v236, v[62:65], s[36:37] offset:0
	s_waitcnt vmcnt(31)
	v_lshlrev_b32_e32 v240, 16, v194
	v_and_b32_e32 v241, 0xffff0000, v194
	v_lshlrev_b32_e32 v242, 16, v195
	v_and_b32_e32 v243, 0xffff0000, v195
	v_pk_mul_f32 v[58:59], v[58:59], v[240:241]
	v_pk_mul_f32 v[60:61], v[60:61], v[242:243]
	global_store_dwordx4 v236, v[58:61], s[36:37] offset:64
	s_waitcnt vmcnt(31)
	v_lshlrev_b32_e32 v240, 16, v196
	v_and_b32_e32 v241, 0xffff0000, v196
	v_lshlrev_b32_e32 v242, 16, v197
	v_and_b32_e32 v243, 0xffff0000, v197
	v_pk_mul_f32 v[54:55], v[54:55], v[240:241]
	v_pk_mul_f32 v[56:57], v[56:57], v[242:243]
	global_store_dwordx4 v236, v[54:57], s[36:37] offset:512
	s_waitcnt vmcnt(31)
	v_lshlrev_b32_e32 v240, 16, v198
	v_and_b32_e32 v241, 0xffff0000, v198
	v_lshlrev_b32_e32 v242, 16, v199
	v_and_b32_e32 v243, 0xffff0000, v199
	v_pk_mul_f32 v[50:51], v[50:51], v[240:241]
	v_pk_mul_f32 v[52:53], v[52:53], v[242:243]
	global_store_dwordx4 v236, v[50:53], s[36:37] offset:576
	s_waitcnt vmcnt(31)
; __device__ __forceinline__ float bfl(unsigned w) { return __uint_as_float(w << 16); }
; __device__ __forceinline__ float bfh(unsigned w) { return __uint_as_float(w & 0xffff0000u); }
;     __device__ __forceinline__ void operator()(const f32x4 (&acc)[2][2][4][2], const Unit& u, int wr, int wc, int fr, int fq) const {
;     ...
;         for (int ai = 0; ai < 2; ++ai)
; #pragma unroll
;             for (int m = 0; m < 4; ++m) { const size_t ro = (size_t)(row0 + ai * HALF + m * 16) * D + col0;
; #pragma unroll
;                 for (int bj = 0; bj < 2; ++bj)
; #pragma unroll
;                     for (int n = 0; n < 2; ++n) { const size_t o = ro + bj * HALF + n * 16;
;                         const u32x2 gw = *(const u32x2*)(G + o); const f32x4 g = (f32x4){bfl(gw.x), bfh(gw.x), bfl(gw.y), bfh(gw.y)};
;                         *(f32x4*)(C + o) = g * acc[ai][bj][m][n]; }
;                 asm volatile("" ::: "memory"); }
;     }
	v_lshlrev_b32_e32 v240, 16, v200
	v_and_b32_e32 v241, 0xffff0000, v200
	v_lshlrev_b32_e32 v242, 16, v201
	v_and_b32_e32 v243, 0xffff0000, v201
	v_pk_mul_f32 v[46:47], v[46:47], v[240:241]
	v_pk_mul_f32 v[48:49], v[48:49], v[242:243]
	global_store_dwordx4 v237, v[46:49], s[36:37] offset:0
	s_waitcnt vmcnt(31)
	v_lshlrev_b32_e32 v240, 16, v202
	v_and_b32_e32 v241, 0xffff0000, v202
	v_lshlrev_b32_e32 v242, 16, v203
	v_and_b32_e32 v243, 0xffff0000, v203
	v_pk_mul_f32 v[42:43], v[42:43], v[240:241]
	v_pk_mul_f32 v[44:45], v[44:45], v[242:243]
	global_store_dwordx4 v237, v[42:45], s[36:37] offset:64
	s_waitcnt vmcnt(31)
	v_lshlrev_b32_e32 v240, 16, v204
	v_and_b32_e32 v241, 0xffff0000, v204
	v_lshlrev_b32_e32 v242, 16, v205
	v_and_b32_e32 v243, 0xffff0000, v205
	v_pk_mul_f32 v[38:39], v[38:39], v[240:241]
	v_pk_mul_f32 v[40:41], v[40:41], v[242:243]
	global_store_dwordx4 v237, v[38:41], s[36:37] offset:512
	s_waitcnt vmcnt(31)
	v_lshlrev_b32_e32 v240, 16, v206
	v_and_b32_e32 v241, 0xffff0000, v206
	v_lshlrev_b32_e32 v242, 16, v207
	v_and_b32_e32 v243, 0xffff0000, v207
	v_pk_mul_f32 v[34:35], v[34:35], v[240:241]
	v_pk_mul_f32 v[36:37], v[36:37], v[242:243]
	global_store_dwordx4 v237, v[34:37], s[36:37] offset:576
	s_waitcnt vmcnt(31)
	v_lshlrev_b32_e32 v240, 16, v208
	v_and_b32_e32 v241, 0xffff0000, v208
	v_lshlrev_b32_e32 v242, 16, v209
	v_and_b32_e32 v243, 0xffff0000, v209
	v_pk_mul_f32 v[30:31], v[30:31], v[240:241]
	v_pk_mul_f32 v[32:33], v[32:33], v[242:243]
	global_store_dwordx4 v238, v[30:33], s[36:37] offset:0
	s_waitcnt vmcnt(31)
	v_lshlrev_b32_e32 v240, 16, v210
	v_and_b32_e32 v241, 0xffff0000, v210
	v_lshlrev_b32_e32 v242, 16, v211
	v_and_b32_e32 v243, 0xffff0000, v211
	v_pk_mul_f32 v[26:27], v[26:27], v[240:241]
	v_pk_mul_f32 v[28:29], v[28:29], v[242:243]
	global_store_dwordx4 v238, v[26:29], s[36:37] offset:64
	s_waitcnt vmcnt(31)
	v_lshlrev_b32_e32 v240, 16, v212
	v_and_b32_e32 v241, 0xffff0000, v212
	v_lshlrev_b32_e32 v242, 16, v213
	v_and_b32_e32 v243, 0xffff0000, v213
	v_pk_mul_f32 v[22:23], v[22:23], v[240:241]
	v_pk_mul_f32 v[24:25], v[24:25], v[242:243]
	global_store_dwordx4 v238, v[22:25], s[36:37] offset:512
	s_waitcnt vmcnt(31)
	v_lshlrev_b32_e32 v240, 16, v214
	v_and_b32_e32 v241, 0xffff0000, v214
	v_lshlrev_b32_e32 v242, 16, v215
	v_and_b32_e32 v243, 0xffff0000, v215
	v_pk_mul_f32 v[18:19], v[18:19], v[240:241]
	v_pk_mul_f32 v[20:21], v[20:21], v[242:243]
	global_store_dwordx4 v238, v[18:21], s[36:37] offset:576
	s_waitcnt vmcnt(31)
	v_lshlrev_b32_e32 v240, 16, v216
	v_and_b32_e32 v241, 0xffff0000, v216
	v_lshlrev_b32_e32 v242, 16, v217
	v_and_b32_e32 v243, 0xffff0000, v217
	v_pk_mul_f32 v[14:15], v[14:15], v[240:241]
	v_pk_mul_f32 v[16:17], v[16:17], v[242:243]
	global_store_dwordx4 v239, v[14:17], s[36:37] offset:0
	s_waitcnt vmcnt(31)
	v_lshlrev_b32_e32 v240, 16, v218
	v_and_b32_e32 v241, 0xffff0000, v218
	v_lshlrev_b32_e32 v242, 16, v219
	v_and_b32_e32 v243, 0xffff0000, v219
	v_pk_mul_f32 v[10:11], v[10:11], v[240:241]
	v_pk_mul_f32 v[12:13], v[12:13], v[242:243]
	global_store_dwordx4 v239, v[10:13], s[36:37] offset:64
	s_waitcnt vmcnt(31)
	v_lshlrev_b32_e32 v240, 16, v220
	v_and_b32_e32 v241, 0xffff0000, v220
	v_lshlrev_b32_e32 v242, 16, v221
	v_and_b32_e32 v243, 0xffff0000, v221
	v_pk_mul_f32 v[6:7], v[6:7], v[240:241]
	v_pk_mul_f32 v[8:9], v[8:9], v[242:243]
	global_store_dwordx4 v239, v[6:9], s[36:37] offset:512
	s_waitcnt vmcnt(31)
	v_lshlrev_b32_e32 v240, 16, v222
	v_and_b32_e32 v241, 0xffff0000, v222
	v_lshlrev_b32_e32 v242, 16, v223
	v_and_b32_e32 v243, 0xffff0000, v223
	v_pk_mul_f32 v[2:3], v[2:3], v[240:241]
	v_pk_mul_f32 v[4:5], v[4:5], v[242:243]
	global_store_dwordx4 v239, v[2:5], s[36:37] offset:576
	s_mov_b64 s[38:39], 0x58000
	s_cbranch_vccnz .LBB0_1213
	s_andn2_b64 vcc, exec, s[14:15]
	s_cbranch_vccnz .LBB0_1212
	s_barrier
	s_branch .LBB0_1212
